# two more mid-burst vmcnt(0) waits relaxed to counted waits (mseq item head igfg loads; stage_wig loads)
# baseline (speedup 1.0000x reference)
; #define LAS __attribute__((address_space(3)))
; __device__ __forceinline__ float rdlane(float v, int l) { return __builtin_bit_cast(float, __builtin_amdgcn_readlane(__builtin_bit_cast(int, v), l)); }
; __device__ __forceinline__ float bperm(float v, int srclane) { return __builtin_bit_cast(float, __builtin_amdgcn_ds_bpermute(srclane << 2, __builtin_bit_cast(int, v))); }
; __device__ __forceinline__ float log_sigmoid(float x) { return fminf(x, 0.f) - log1pf(expf(-fabsf(x))); }
; __device__ __forceinline__ void mseq_item(Frame& F, int L, int item) {
;     const int bh = item >> 3, vs = item & 7, b = bh >> 2, h = bh & 3;
;     LAS float* sg = (LAS float*)(F.lds + SQ_G); LAS float* sbend = (LAS float*)(F.lds + SQ_SC); LAS float* sgmax = sbend + 32; LAS float* sdec = sbend + 64; LAS float* smn = sbend + 96;
;     const float* igfg = WSP(float, WS_IGFG);
;     { float igv[4], fgv[4];
; #pragma unroll
;       for (int i = 0; i < 4; ++i) { const int m = b * SEQ + (4 * F.wave + i) * 64 + F.lane; igv[i] = igfg[(size_t)m * 8 + h]; fgv[i] = igfg[(size_t)m * 8 + 4 + h]; }
; #pragma unroll
;       for (int i = 0; i < 4; ++i) { const int c = 4 * F.wave + i;
;         float bc = log_sigmoid(fgv[i]);
; #pragma unroll
;         for (int o = 1; o < 64; o <<= 1) { const float t = bperm(bc, F.lane - o); if (F.lane >= o) bc += t; }
;         const float bend = rdlane(bc, 63); const float g = igv[i] + bend - bc; const float gm = wave_max(g);
;         sg[c * 64 + F.lane] = g; if (F.lane == 0) { sbend[c] = bend; sgmax[c] = gm; } } }
.LBB0_626:
	s_ashr_i32 s12, s75, 3
	s_lshl_b32 s18, s75, 6
	s_and_b32 s19, s12, 3
	s_and_b32 s76, s18, 0xfffff800
	v_add_u32_e32 v4, s76, v3
	s_lshl_b32 s8, s19, 2
	s_add_u32 s14, s28, s8
	v_ashrrev_i32_e32 v5, 31, v4
	s_addc_u32 s15, s29, 0
	v_lshlrev_b64 v[6:7], 5, v[4:5]
	v_lshl_add_u64 v[6:7], s[14:15], 0, v[6:7]
	global_load_dword v10, v[6:7], off
	global_load_dword v14, v[6:7], off offset:16
	v_add_u32_e32 v6, 64, v4
	v_ashrrev_i32_e32 v7, 31, v6
	v_lshlrev_b64 v[6:7], 5, v[6:7]
	v_lshl_add_u64 v[6:7], s[14:15], 0, v[6:7]
	global_load_dword v8, v[6:7], off
	global_load_dword v9, v[6:7], off offset:16
	v_add_u32_e32 v6, 0x80, v4
	s_waitcnt vmcnt(4)
	v_add_u32_e32 v12, 0xc0, v4
	v_ashrrev_i32_e32 v7, 31, v6
	v_ashrrev_i32_e32 v13, 31, v12
	v_lshlrev_b64 v[6:7], 5, v[6:7]
	v_lshlrev_b64 v[12:13], 5, v[12:13]
	v_lshl_add_u64 v[6:7], s[14:15], 0, v[6:7]
	v_lshl_add_u64 v[12:13], s[14:15], 0, v[12:13]
	global_load_dword v5, v[6:7], off
	s_nop 0
	global_load_dword v7, v[6:7], off offset:16
	s_nop 0
	global_load_dword v4, v[12:13], off
	global_load_dword v6, v[12:13], off offset:16
	s_mov_b32 s8, 0xb2a5705f
	s_waitcnt vmcnt(0)
	v_mul_f32_e64 v12, |v14|, s97
	v_fma_f32 v13, |v14|, s97, -v12
	v_rndne_f32_e32 v15, v12
	v_fma_f32 v13, |v14|, s8, v13
	v_sub_f32_e32 v12, v12, v15
	v_add_f32_e32 v12, v12, v13
	v_exp_f32_e32 v12, v12
	v_cvt_i32_f32_e32 v13, v15
	s_mov_b32 s8, 0x42ce8ed0
	v_cmp_ngt_f32_e64 vcc, |v14|, s8
	s_mov_b32 s8, 0xc2b17218
	v_ldexp_f32 v12, v12, v13
	v_cndmask_b32_e32 v12, 0, v12, vcc
	v_cmp_nlt_f32_e64 vcc, |v14|, s8
	v_max_f32_e32 v11, v14, v14
	s_mov_b32 s8, 0x3f2aaaab
	v_cndmask_b32_e32 v12, v247, v12, vcc
	v_add_f32_e32 v13, 1.0, v12
	v_add_f32_e32 v14, -1.0, v13
	v_sub_f32_e32 v15, v14, v13
	v_add_f32_e32 v15, 1.0, v15
	v_sub_f32_e32 v14, v12, v14
	v_add_f32_e32 v16, v14, v15
	v_frexp_mant_f32_e32 v14, v13
	v_cmp_gt_f32_e32 vcc, s8, v14
	v_cvt_f64_f32_e32 v[14:15], v13
	v_frexp_exp_i32_f64_e32 v14, v[14:15]
	v_subbrev_co_u32_e32 v14, vcc, 0, v14, vcc
	v_sub_u32_e32 v15, 0, v14
	v_ldexp_f32 v13, v13, v15
	v_ldexp_f32 v15, v16, v15
	v_add_f32_e32 v16, -1.0, v13
	v_add_f32_e32 v17, 1.0, v16
	v_sub_f32_e32 v17, v13, v17
	v_add_f32_e32 v17, v15, v17
	v_add_f32_e32 v18, v16, v17
	v_sub_f32_e32 v16, v16, v18
	v_add_f32_e32 v16, v17, v16
	v_add_f32_e32 v17, 1.0, v13
	v_add_f32_e32 v19, -1.0, v17
	v_sub_f32_e32 v13, v13, v19
	v_add_f32_e32 v13, v15, v13
	v_add_f32_e32 v15, v17, v13
	v_sub_f32_e32 v17, v17, v15
	v_add_f32_e32 v13, v13, v17
	v_rcp_f32_e32 v17, v15
	v_cvt_f32_i32_e32 v14, v14
	s_mov_b32 s8, 0x3f317218
	v_min_f32_e32 v11, 0, v11
	v_mul_f32_e32 v19, v18, v17
	v_mul_f32_e32 v20, v15, v19
	v_fma_f32 v21, v19, v15, -v20
	v_fmac_f32_e32 v21, v19, v13
	v_add_f32_e32 v22, v20, v21
	v_sub_f32_e32 v23, v18, v22
	v_sub_f32_e32 v18, v18, v23
	v_sub_f32_e32 v20, v22, v20
	v_sub_f32_e32 v18, v18, v22
	v_add_f32_e32 v16, v16, v18
	v_sub_f32_e32 v18, v20, v21
	v_add_f32_e32 v16, v18, v16
	v_add_f32_e32 v18, v23, v16
	v_mul_f32_e32 v20, v17, v18
	v_mul_f32_e32 v21, v15, v20
	v_fma_f32 v15, v20, v15, -v21
	v_fmac_f32_e32 v15, v20, v13
	v_sub_f32_e32 v13, v23, v18
	v_add_f32_e32 v13, v16, v13
	v_add_f32_e32 v16, v21, v15
	v_sub_f32_e32 v22, v18, v16
	v_sub_f32_e32 v18, v18, v22
	v_sub_f32_e32 v21, v16, v21
	v_sub_f32_e32 v16, v18, v16
	v_add_f32_e32 v13, v13, v16
	v_sub_f32_e32 v15, v21, v15
	v_add_f32_e32 v13, v15, v13
	v_add_f32_e32 v15, v19, v20
	v_add_f32_e32 v13, v22, v13
	v_sub_f32_e32 v16, v15, v19
	v_mul_f32_e32 v13, v17, v13
	v_sub_f32_e32 v16, v20, v16
	v_add_f32_e32 v13, v16, v13
	v_mul_f32_e32 v19, 0x3f317218, v14
	v_add_f32_e32 v16, v15, v13
	v_fma_f32 v20, v14, s8, -v19
	v_mul_f32_e32 v17, v16, v16
	v_fmac_f32_e32 v20, 0xb102e308, v14
	v_sub_f32_e32 v14, v16, v15
	v_fmamk_f32 v18, v17, 0x3e9b6dac, v227
	v_sub_f32_e32 v13, v13, v14
	v_add_f32_e32 v14, v19, v20
	v_fmaak_f32 v18, v17, v18, 0x3f2aaada
	v_sub_f32_e32 v15, v14, v19
	v_ldexp_f32 v19, v16, 1
	v_mul_f32_e32 v16, v16, v17
	v_mul_f32_e32 v16, v16, v18
	v_add_f32_e32 v17, v19, v16
	v_sub_f32_e32 v18, v17, v19
	v_ldexp_f32 v13, v13, 1
	v_sub_f32_e32 v16, v16, v18
	v_add_f32_e32 v13, v13, v16
	v_add_f32_e32 v16, v17, v13
	v_sub_f32_e32 v17, v16, v17
	v_sub_f32_e32 v13, v13, v17
	v_add_f32_e32 v17, v14, v16
	v_sub_f32_e32 v18, v17, v14
	v_sub_f32_e32 v19, v17, v18
	v_sub_f32_e32 v15, v20, v15
	v_sub_f32_e32 v14, v14, v19
	v_sub_f32_e32 v16, v16, v18
	v_add_f32_e32 v14, v16, v14
	v_add_f32_e32 v16, v15, v13
	v_sub_f32_e32 v18, v16, v15
	v_sub_f32_e32 v19, v16, v18
	v_sub_f32_e32 v15, v15, v19
	v_sub_f32_e32 v13, v13, v18
	v_add_f32_e32 v14, v16, v14
	v_add_f32_e32 v13, v13, v15
	v_add_f32_e32 v15, v17, v14
	v_sub_f32_e32 v16, v15, v17
	v_sub_f32_e32 v14, v14, v16
	v_add_f32_e32 v13, v13, v14
	s_mov_b32 s8, 0x7f800000
	v_add_f32_e32 v13, v15, v13
	v_cmp_neq_f32_e32 vcc, s8, v12
	s_mov_b32 s8, 0x33800000
	s_nop 0
	v_cndmask_b32_e32 v13, v247, v13, vcc
	v_cmp_lt_f32_e64 vcc, |v12|, s8
	s_nop 1
	v_cndmask_b32_e32 v12, v13, v12, vcc
	v_sub_f32_e32 v11, v11, v12
	ds_bpermute_b32 v12, v77, v11
	s_waitcnt lgkmcnt(0)
	v_add_f32_e32 v12, v11, v12
	v_cndmask_b32_e64 v11, v12, v11, s[42:43]
	ds_bpermute_b32 v12, v101, v11
	s_waitcnt lgkmcnt(0)
	v_add_f32_e32 v12, v11, v12
	v_cndmask_b32_e64 v11, v12, v11, s[44:45]
	ds_bpermute_b32 v12, v103, v11
	s_waitcnt lgkmcnt(0)
	v_add_f32_e32 v12, v11, v12
	v_cndmask_b32_e64 v11, v12, v11, s[46:47]
	ds_bpermute_b32 v12, v110, v11
	s_waitcnt lgkmcnt(0)
	v_add_f32_e32 v12, v11, v12
	v_cndmask_b32_e64 v11, v12, v11, s[48:49]
	ds_bpermute_b32 v12, v111, v11
	s_waitcnt lgkmcnt(0)
; __device__ __forceinline__ float rdlane(float v, int l) { return __builtin_bit_cast(float, __builtin_amdgcn_readlane(__builtin_bit_cast(int, v), l)); }
; __device__ __forceinline__ float bperm(float v, int srclane) { return __builtin_bit_cast(float, __builtin_amdgcn_ds_bpermute(srclane << 2, __builtin_bit_cast(int, v))); }
; __device__ __forceinline__ float log_sigmoid(float x) { return fminf(x, 0.f) - log1pf(expf(-fabsf(x))); }
; __device__ __forceinline__ void mseq_item(Frame& F, int L, int item) {
;     ...
;       for (int i = 0; i < 4; ++i) { const int c = 4 * F.wave + i;
;         float bc = log_sigmoid(fgv[i]);
; #pragma unroll
;         for (int o = 1; o < 64; o <<= 1) { const float t = bperm(bc, F.lane - o); if (F.lane >= o) bc += t; }
;         const float bend = rdlane(bc, 63); const float g = igv[i] + bend - bc; const float gm = wave_max(g);
;         sg[c * 64 + F.lane] = g; if (F.lane == 0) { sbend[c] = bend; sgmax[c] = gm; } } }
	v_add_f32_e32 v12, v11, v12
	v_cndmask_b32_e64 v11, v12, v11, s[50:51]
	ds_bpermute_b32 v12, v112, v11
	s_waitcnt lgkmcnt(0)
	v_add_f32_e32 v12, v11, v12
	v_cndmask_b32_e64 v11, v12, v11, s[52:53]
	s_nop 0
	v_readlane_b32 s8, v11, 63
	s_nop 1
	v_add_f32_e32 v10, s8, v10
	v_sub_f32_e32 v10, v10, v11
	v_mov_b32_e32 v11, v10
	s_nop 1
	v_mov_b32_dpp v11, v11 quad_perm:[1,0,3,2] row_mask:0xf bank_mask:0xf
	v_max_f32_e32 v11, v11, v11
	v_max_f32_e32 v11, v10, v11
	v_mov_b32_e32 v12, v11
	s_nop 1
	v_mov_b32_dpp v12, v12 quad_perm:[2,3,0,1] row_mask:0xf bank_mask:0xf
	v_max_f32_e32 v12, v12, v12
	v_max_f32_e32 v11, v11, v12
	v_mov_b32_e32 v12, v11
	s_nop 1
	v_mov_b32_dpp v12, v12 row_half_mirror row_mask:0xf bank_mask:0xf
	v_max_f32_e32 v12, v12, v12
	v_max_f32_e32 v11, v11, v12
	v_mov_b32_e32 v12, v11
	s_nop 1
	v_mov_b32_dpp v12, v12 row_mirror row_mask:0xf bank_mask:0xf
	v_max_f32_e32 v12, v12, v12
	v_max_f32_e32 v11, v11, v12
	v_mov_b32_e32 v12, v11
	s_nop 1
	v_mov_b32_dpp v12, v12 row_bcast:15 row_mask:0xa bank_mask:0xf
	v_max_f32_e32 v12, v12, v12
	v_max_f32_e32 v11, v11, v12
	v_mov_b32_e32 v12, v11
	s_nop 1
	v_mov_b32_dpp v12, v12 row_bcast:31 row_mask:0xc bank_mask:0xf
	v_max_f32_e32 v12, v12, v12
	v_max_f32_e32 v11, v11, v12
	s_nop 0
	v_readlane_b32 s13, v11, 63
	v_add_u32_e32 v11, s34, v75
	ds_write_b32 v11, v10 offset:45056
	s_and_saveexec_b64 s[14:15], s[40:41]
	v_mov_b32_e32 v10, s35
	v_mov_b32_e32 v11, s8
	v_mov_b32_e32 v12, s13
	v_add_u32_e32 v10, 0xd000, v10
	ds_write2_b32 v10, v11, v12 offset1:32
	s_or_b64 exec, exec, s[14:15]
	v_mul_f32_e64 v10, |v9|, s97
	v_rndne_f32_e32 v11, v10
	v_sub_f32_e32 v12, v10, v11
	v_fma_f32 v10, |v9|, s97, -v10
	s_mov_b32 s8, 0xb2a5705f
	v_fma_f32 v10, |v9|, s8, v10
	v_add_f32_e32 v10, v12, v10
	v_exp_f32_e32 v10, v10
	v_cvt_i32_f32_e32 v11, v11
	s_mov_b32 s8, 0x42ce8ed0
	v_cmp_ngt_f32_e64 vcc, |v9|, s8
	s_mov_b32 s8, 0xc2b17218
	v_ldexp_f32 v10, v10, v11
	v_cndmask_b32_e32 v10, 0, v10, vcc
	v_cmp_nlt_f32_e64 vcc, |v9|, s8
	v_max_f32_e32 v12, v9, v9
	s_mov_b32 s8, 0x3f2aaaab
	v_cndmask_b32_e32 v9, v247, v10, vcc
	v_add_f32_e32 v13, 1.0, v9
	v_add_f32_e32 v10, -1.0, v13
	v_sub_f32_e32 v11, v10, v13
	v_add_f32_e32 v11, 1.0, v11
	v_sub_f32_e32 v10, v9, v10
	v_add_f32_e32 v14, v10, v11
	v_frexp_mant_f32_e32 v15, v13
	v_cvt_f64_f32_e32 v[10:11], v13
	v_frexp_exp_i32_f64_e32 v10, v[10:11]
	v_cmp_gt_f32_e32 vcc, s8, v15
	s_mov_b32 s8, 0x3f317218
	v_min_f32_e32 v12, 0, v12
	v_subbrev_co_u32_e32 v10, vcc, 0, v10, vcc
	v_sub_u32_e32 v11, 0, v10
	v_ldexp_f32 v13, v13, v11
	v_ldexp_f32 v11, v14, v11
	v_add_f32_e32 v14, -1.0, v13
	v_add_f32_e32 v17, 1.0, v13
	v_add_f32_e32 v15, 1.0, v14
	v_add_f32_e32 v18, -1.0, v17
	v_sub_f32_e32 v15, v13, v15
	v_sub_f32_e32 v13, v13, v18
	v_add_f32_e32 v15, v11, v15
	v_add_f32_e32 v11, v11, v13
	v_add_f32_e32 v13, v17, v11
	v_rcp_f32_e32 v18, v13
	v_add_f32_e32 v16, v14, v15
	v_sub_f32_e32 v14, v14, v16
	v_add_f32_e32 v14, v15, v14
	v_sub_f32_e32 v15, v17, v13
	v_add_f32_e32 v11, v11, v15
	v_mul_f32_e32 v15, v16, v18
	v_mul_f32_e32 v17, v13, v15
	v_fma_f32 v19, v15, v13, -v17
	v_fmac_f32_e32 v19, v15, v11
	v_add_f32_e32 v20, v17, v19
	v_sub_f32_e32 v21, v16, v20
	v_sub_f32_e32 v16, v16, v21
	v_sub_f32_e32 v17, v20, v17
	v_sub_f32_e32 v16, v16, v20
	v_add_f32_e32 v14, v14, v16
	v_sub_f32_e32 v16, v17, v19
	v_add_f32_e32 v14, v16, v14
	v_add_f32_e32 v16, v21, v14
	v_mul_f32_e32 v17, v18, v16
	v_mul_f32_e32 v19, v13, v17
	v_fma_f32 v13, v17, v13, -v19
	v_fmac_f32_e32 v13, v17, v11
	v_sub_f32_e32 v11, v21, v16
	v_add_f32_e32 v11, v14, v11
	v_add_f32_e32 v14, v19, v13
	v_sub_f32_e32 v20, v16, v14
	v_sub_f32_e32 v16, v16, v20
	v_sub_f32_e32 v19, v14, v19
	v_sub_f32_e32 v14, v16, v14
	v_add_f32_e32 v11, v11, v14
	v_sub_f32_e32 v13, v19, v13
	v_cvt_f32_i32_e32 v10, v10
	v_add_f32_e32 v11, v13, v11
	v_add_f32_e32 v13, v15, v17
	v_add_f32_e32 v11, v20, v11
	v_sub_f32_e32 v14, v13, v15
	v_mul_f32_e32 v11, v18, v11
	v_sub_f32_e32 v14, v17, v14
	v_add_f32_e32 v11, v14, v11
	v_mul_f32_e32 v17, 0x3f317218, v10
	v_add_f32_e32 v14, v13, v11
	v_fma_f32 v18, v10, s8, -v17
	v_mul_f32_e32 v15, v14, v14
	v_fmac_f32_e32 v18, 0xb102e308, v10
	v_sub_f32_e32 v10, v14, v13
	v_fmamk_f32 v16, v15, 0x3e9b6dac, v227
	v_sub_f32_e32 v10, v11, v10
	v_add_f32_e32 v11, v17, v18
	v_fmaak_f32 v16, v15, v16, 0x3f2aaada
	v_sub_f32_e32 v13, v11, v17
	v_ldexp_f32 v17, v14, 1
	v_mul_f32_e32 v14, v14, v15
	v_mul_f32_e32 v14, v14, v16
	v_add_f32_e32 v15, v17, v14
	v_sub_f32_e32 v16, v15, v17
	v_ldexp_f32 v10, v10, 1
	v_sub_f32_e32 v14, v14, v16
	v_add_f32_e32 v10, v10, v14
	v_add_f32_e32 v14, v15, v10
	v_sub_f32_e32 v15, v14, v15
	v_sub_f32_e32 v10, v10, v15
	v_add_f32_e32 v15, v11, v14
	v_sub_f32_e32 v16, v15, v11
	v_sub_f32_e32 v17, v15, v16
	v_sub_f32_e32 v13, v18, v13
	v_sub_f32_e32 v11, v11, v17
	v_sub_f32_e32 v14, v14, v16
	v_add_f32_e32 v11, v14, v11
	v_add_f32_e32 v14, v13, v10
	v_sub_f32_e32 v16, v14, v13
	v_sub_f32_e32 v17, v14, v16
	v_sub_f32_e32 v13, v13, v17
	v_sub_f32_e32 v10, v10, v16
	v_add_f32_e32 v11, v14, v11
	v_add_f32_e32 v10, v10, v13
	v_add_f32_e32 v13, v15, v11
	v_sub_f32_e32 v14, v13, v15
	v_sub_f32_e32 v11, v11, v14
	v_add_f32_e32 v10, v10, v11
	s_mov_b32 s8, 0x7f800000
	v_add_f32_e32 v10, v13, v10
	v_cmp_neq_f32_e32 vcc, s8, v9
	s_mov_b32 s8, 0x33800000
	s_nop 0
	v_cndmask_b32_e32 v10, v247, v10, vcc
	v_cmp_lt_f32_e64 vcc, |v9|, s8
	s_nop 1
	v_cndmask_b32_e32 v9, v10, v9, vcc
	v_sub_f32_e32 v9, v12, v9
	ds_bpermute_b32 v10, v77, v9
	s_waitcnt lgkmcnt(0)
	v_add_f32_e32 v10, v9, v10
	v_cndmask_b32_e64 v9, v10, v9, s[42:43]
	ds_bpermute_b32 v10, v101, v9
	s_waitcnt lgkmcnt(0)
; __device__ __forceinline__ float rdlane(float v, int l) { return __builtin_bit_cast(float, __builtin_amdgcn_readlane(__builtin_bit_cast(int, v), l)); }
; __device__ __forceinline__ float bperm(float v, int srclane) { return __builtin_bit_cast(float, __builtin_amdgcn_ds_bpermute(srclane << 2, __builtin_bit_cast(int, v))); }
; __device__ __forceinline__ float log_sigmoid(float x) { return fminf(x, 0.f) - log1pf(expf(-fabsf(x))); }
; __device__ __forceinline__ void mseq_item(Frame& F, int L, int item) {
;     ...
;       for (int i = 0; i < 4; ++i) { const int c = 4 * F.wave + i;
;         float bc = log_sigmoid(fgv[i]);
; #pragma unroll
;         for (int o = 1; o < 64; o <<= 1) { const float t = bperm(bc, F.lane - o); if (F.lane >= o) bc += t; }
;         const float bend = rdlane(bc, 63); const float g = igv[i] + bend - bc; const float gm = wave_max(g);
;         sg[c * 64 + F.lane] = g; if (F.lane == 0) { sbend[c] = bend; sgmax[c] = gm; } } }
	v_add_f32_e32 v10, v9, v10
	v_cndmask_b32_e64 v9, v10, v9, s[44:45]
	ds_bpermute_b32 v10, v103, v9
	s_waitcnt lgkmcnt(0)
	v_add_f32_e32 v10, v9, v10
	v_cndmask_b32_e64 v9, v10, v9, s[46:47]
	ds_bpermute_b32 v10, v110, v9
	s_waitcnt lgkmcnt(0)
	v_add_f32_e32 v10, v9, v10
	v_cndmask_b32_e64 v9, v10, v9, s[48:49]
	ds_bpermute_b32 v10, v111, v9
	s_waitcnt lgkmcnt(0)
	v_add_f32_e32 v10, v9, v10
	v_cndmask_b32_e64 v9, v10, v9, s[50:51]
	ds_bpermute_b32 v10, v112, v9
	s_waitcnt lgkmcnt(0)
	v_add_f32_e32 v10, v9, v10
	v_cndmask_b32_e64 v9, v10, v9, s[52:53]
	s_nop 0
	v_readlane_b32 s8, v9, 63
	s_nop 1
	v_add_f32_e32 v8, s8, v8
	v_sub_f32_e32 v8, v8, v9
	v_mov_b32_e32 v9, v8
	s_nop 1
	v_mov_b32_dpp v9, v9 quad_perm:[1,0,3,2] row_mask:0xf bank_mask:0xf
	v_max_f32_e32 v9, v9, v9
	v_max_f32_e32 v9, v8, v9
	v_mov_b32_e32 v10, v9
	s_nop 1
	v_mov_b32_dpp v10, v10 quad_perm:[2,3,0,1] row_mask:0xf bank_mask:0xf
	v_max_f32_e32 v10, v10, v10
	v_max_f32_e32 v9, v9, v10
	v_mov_b32_e32 v10, v9
	s_nop 1
	v_mov_b32_dpp v10, v10 row_half_mirror row_mask:0xf bank_mask:0xf
	v_max_f32_e32 v10, v10, v10
	v_max_f32_e32 v9, v9, v10
	v_mov_b32_e32 v10, v9
	s_nop 1
	v_mov_b32_dpp v10, v10 row_mirror row_mask:0xf bank_mask:0xf
	v_max_f32_e32 v10, v10, v10
	v_max_f32_e32 v9, v9, v10
	v_mov_b32_e32 v10, v9
	s_nop 1
	v_mov_b32_dpp v10, v10 row_bcast:15 row_mask:0xa bank_mask:0xf
	v_max_f32_e32 v10, v10, v10
	v_max_f32_e32 v9, v9, v10
	v_mov_b32_e32 v10, v9
	s_nop 1
	v_mov_b32_dpp v10, v10 row_bcast:31 row_mask:0xc bank_mask:0xf
	v_max_f32_e32 v10, v10, v10
	v_max_f32_e32 v9, v9, v10
	s_nop 0
	v_readlane_b32 s13, v9, 63
	v_add_u32_e32 v9, s36, v75
	ds_write_b32 v9, v8 offset:45056
	s_and_saveexec_b64 s[14:15], s[40:41]
	v_mov_b32_e32 v8, s35
	v_mov_b32_e32 v9, s8
	v_mov_b32_e32 v10, s13
	v_add_u32_e32 v8, 0xd000, v8
	ds_write2_b32 v8, v9, v10 offset0:1 offset1:33
	s_or_b64 exec, exec, s[14:15]
	v_mul_f32_e64 v8, |v7|, s97
	v_rndne_f32_e32 v9, v8
	v_sub_f32_e32 v10, v8, v9
	v_fma_f32 v8, |v7|, s97, -v8
	s_mov_b32 s8, 0xb2a5705f
	v_fma_f32 v8, |v7|, s8, v8
	v_add_f32_e32 v8, v10, v8
	v_exp_f32_e32 v8, v8
	v_cvt_i32_f32_e32 v9, v9
	s_mov_b32 s8, 0x42ce8ed0
	v_cmp_ngt_f32_e64 vcc, |v7|, s8
	s_mov_b32 s8, 0xc2b17218
	v_ldexp_f32 v8, v8, v9
	v_cndmask_b32_e32 v8, 0, v8, vcc
	v_cmp_nlt_f32_e64 vcc, |v7|, s8
	v_max_f32_e32 v10, v7, v7
	s_mov_b32 s8, 0x3f2aaaab
	v_cndmask_b32_e32 v7, v247, v8, vcc
	v_add_f32_e32 v11, 1.0, v7
	v_add_f32_e32 v8, -1.0, v11
	v_sub_f32_e32 v9, v8, v11
	v_add_f32_e32 v9, 1.0, v9
	v_sub_f32_e32 v8, v7, v8
	v_add_f32_e32 v12, v8, v9
	v_frexp_mant_f32_e32 v13, v11
	v_cvt_f64_f32_e32 v[8:9], v11
	v_frexp_exp_i32_f64_e32 v8, v[8:9]
	v_cmp_gt_f32_e32 vcc, s8, v13
	s_mov_b32 s8, 0x3f317218
	v_min_f32_e32 v10, 0, v10
	v_subbrev_co_u32_e32 v8, vcc, 0, v8, vcc
	v_sub_u32_e32 v9, 0, v8
	v_ldexp_f32 v11, v11, v9
	v_ldexp_f32 v9, v12, v9
	v_add_f32_e32 v12, -1.0, v11
	v_add_f32_e32 v15, 1.0, v11
	v_add_f32_e32 v13, 1.0, v12
	v_add_f32_e32 v16, -1.0, v15
	v_sub_f32_e32 v13, v11, v13
	v_sub_f32_e32 v11, v11, v16
	v_add_f32_e32 v13, v9, v13
	v_add_f32_e32 v9, v9, v11
	v_add_f32_e32 v11, v15, v9
	v_rcp_f32_e32 v16, v11
	v_add_f32_e32 v14, v12, v13
	v_sub_f32_e32 v12, v12, v14
	v_add_f32_e32 v12, v13, v12
	v_sub_f32_e32 v13, v15, v11
	v_add_f32_e32 v9, v9, v13
	v_mul_f32_e32 v13, v14, v16
	v_mul_f32_e32 v15, v11, v13
	v_fma_f32 v17, v13, v11, -v15
	v_fmac_f32_e32 v17, v13, v9
	v_add_f32_e32 v18, v15, v17
	v_sub_f32_e32 v19, v14, v18
	v_sub_f32_e32 v14, v14, v19
	v_sub_f32_e32 v15, v18, v15
	v_sub_f32_e32 v14, v14, v18
	v_add_f32_e32 v12, v12, v14
	v_sub_f32_e32 v14, v15, v17
	v_add_f32_e32 v12, v14, v12
	v_add_f32_e32 v14, v19, v12
	v_mul_f32_e32 v15, v16, v14
	v_mul_f32_e32 v17, v11, v15
	v_fma_f32 v11, v15, v11, -v17
	v_fmac_f32_e32 v11, v15, v9
	v_sub_f32_e32 v9, v19, v14
	v_add_f32_e32 v9, v12, v9
	v_add_f32_e32 v12, v17, v11
	v_sub_f32_e32 v18, v14, v12
	v_sub_f32_e32 v14, v14, v18
	v_sub_f32_e32 v17, v12, v17
	v_sub_f32_e32 v12, v14, v12
	v_add_f32_e32 v9, v9, v12
	v_sub_f32_e32 v11, v17, v11
	v_cvt_f32_i32_e32 v8, v8
	v_add_f32_e32 v9, v11, v9
	v_add_f32_e32 v11, v13, v15
	v_add_f32_e32 v9, v18, v9
	v_sub_f32_e32 v12, v11, v13
	v_mul_f32_e32 v9, v16, v9
	v_sub_f32_e32 v12, v15, v12
	v_add_f32_e32 v9, v12, v9
	v_mul_f32_e32 v15, 0x3f317218, v8
	v_add_f32_e32 v12, v11, v9
	v_fma_f32 v16, v8, s8, -v15
	v_mul_f32_e32 v13, v12, v12
	v_fmac_f32_e32 v16, 0xb102e308, v8
	v_sub_f32_e32 v8, v12, v11
	v_fmamk_f32 v14, v13, 0x3e9b6dac, v227
	v_sub_f32_e32 v8, v9, v8
	v_add_f32_e32 v9, v15, v16
	v_fmaak_f32 v14, v13, v14, 0x3f2aaada
	v_sub_f32_e32 v11, v9, v15
	v_ldexp_f32 v15, v12, 1
	v_mul_f32_e32 v12, v12, v13
	v_mul_f32_e32 v12, v12, v14
	v_add_f32_e32 v13, v15, v12
	v_sub_f32_e32 v14, v13, v15
	v_ldexp_f32 v8, v8, 1
	v_sub_f32_e32 v12, v12, v14
	v_add_f32_e32 v8, v8, v12
	v_add_f32_e32 v12, v13, v8
	v_sub_f32_e32 v13, v12, v13
	v_sub_f32_e32 v8, v8, v13
	v_add_f32_e32 v13, v9, v12
	v_sub_f32_e32 v14, v13, v9
	v_sub_f32_e32 v15, v13, v14
	v_sub_f32_e32 v11, v16, v11
	v_sub_f32_e32 v9, v9, v15
	v_sub_f32_e32 v12, v12, v14
	v_add_f32_e32 v9, v12, v9
	v_add_f32_e32 v12, v11, v8
	v_sub_f32_e32 v14, v12, v11
	v_sub_f32_e32 v15, v12, v14
	v_sub_f32_e32 v11, v11, v15
	v_sub_f32_e32 v8, v8, v14
	v_add_f32_e32 v9, v12, v9
	v_add_f32_e32 v8, v8, v11
	v_add_f32_e32 v11, v13, v9
	v_sub_f32_e32 v12, v11, v13
	v_sub_f32_e32 v9, v9, v12
	v_add_f32_e32 v8, v8, v9
	s_mov_b32 s8, 0x7f800000
	v_add_f32_e32 v8, v11, v8
	v_cmp_neq_f32_e32 vcc, s8, v7
	s_mov_b32 s8, 0x33800000
	s_nop 0
	v_cndmask_b32_e32 v8, v247, v8, vcc
	v_cmp_lt_f32_e64 vcc, |v7|, s8
	s_nop 1
	v_cndmask_b32_e32 v7, v8, v7, vcc
	v_sub_f32_e32 v7, v10, v7
	ds_bpermute_b32 v8, v77, v7
	s_waitcnt lgkmcnt(0)
; __device__ __forceinline__ float rdlane(float v, int l) { return __builtin_bit_cast(float, __builtin_amdgcn_readlane(__builtin_bit_cast(int, v), l)); }
; __device__ __forceinline__ float bperm(float v, int srclane) { return __builtin_bit_cast(float, __builtin_amdgcn_ds_bpermute(srclane << 2, __builtin_bit_cast(int, v))); }
; __device__ __forceinline__ float log_sigmoid(float x) { return fminf(x, 0.f) - log1pf(expf(-fabsf(x))); }
; __device__ __forceinline__ void mseq_item(Frame& F, int L, int item) {
;     ...
;       for (int i = 0; i < 4; ++i) { const int c = 4 * F.wave + i;
;         float bc = log_sigmoid(fgv[i]);
; #pragma unroll
;         for (int o = 1; o < 64; o <<= 1) { const float t = bperm(bc, F.lane - o); if (F.lane >= o) bc += t; }
;         const float bend = rdlane(bc, 63); const float g = igv[i] + bend - bc; const float gm = wave_max(g);
;         sg[c * 64 + F.lane] = g; if (F.lane == 0) { sbend[c] = bend; sgmax[c] = gm; } } }
	v_add_f32_e32 v8, v7, v8
	v_cndmask_b32_e64 v7, v8, v7, s[42:43]
	ds_bpermute_b32 v8, v101, v7
	s_waitcnt lgkmcnt(0)
	v_add_f32_e32 v8, v7, v8
	v_cndmask_b32_e64 v7, v8, v7, s[44:45]
	ds_bpermute_b32 v8, v103, v7
	s_waitcnt lgkmcnt(0)
	v_add_f32_e32 v8, v7, v8
	v_cndmask_b32_e64 v7, v8, v7, s[46:47]
	ds_bpermute_b32 v8, v110, v7
	s_waitcnt lgkmcnt(0)
	v_add_f32_e32 v8, v7, v8
	v_cndmask_b32_e64 v7, v8, v7, s[48:49]
	ds_bpermute_b32 v8, v111, v7
	s_waitcnt lgkmcnt(0)
	v_add_f32_e32 v8, v7, v8
	v_cndmask_b32_e64 v7, v8, v7, s[50:51]
	ds_bpermute_b32 v8, v112, v7
	s_waitcnt lgkmcnt(0)
	v_add_f32_e32 v8, v7, v8
	v_cndmask_b32_e64 v7, v8, v7, s[52:53]
	s_nop 0
	v_readlane_b32 s8, v7, 63
	s_nop 1
	v_add_f32_e32 v5, s8, v5
	v_sub_f32_e32 v5, v5, v7
	v_mov_b32_e32 v7, v5
	s_nop 1
	v_mov_b32_dpp v7, v7 quad_perm:[1,0,3,2] row_mask:0xf bank_mask:0xf
	v_max_f32_e32 v7, v7, v7
	v_max_f32_e32 v7, v5, v7
	v_mov_b32_e32 v8, v7
	s_nop 1
	v_mov_b32_dpp v8, v8 quad_perm:[2,3,0,1] row_mask:0xf bank_mask:0xf
	v_max_f32_e32 v8, v8, v8
	v_max_f32_e32 v7, v7, v8
	v_mov_b32_e32 v8, v7
	s_nop 1
	v_mov_b32_dpp v8, v8 row_half_mirror row_mask:0xf bank_mask:0xf
	v_max_f32_e32 v8, v8, v8
	v_max_f32_e32 v7, v7, v8
	v_mov_b32_e32 v8, v7
	s_nop 1
	v_mov_b32_dpp v8, v8 row_mirror row_mask:0xf bank_mask:0xf
	v_max_f32_e32 v8, v8, v8
	v_max_f32_e32 v7, v7, v8
	v_mov_b32_e32 v8, v7
	s_nop 1
	v_mov_b32_dpp v8, v8 row_bcast:15 row_mask:0xa bank_mask:0xf
	v_max_f32_e32 v8, v8, v8
	v_max_f32_e32 v7, v7, v8
	v_mov_b32_e32 v8, v7
	s_nop 1
	v_mov_b32_dpp v8, v8 row_bcast:31 row_mask:0xc bank_mask:0xf
	v_max_f32_e32 v8, v8, v8
	v_max_f32_e32 v7, v7, v8
	s_nop 0
	v_readlane_b32 s13, v7, 63
	v_add_u32_e32 v7, s37, v75
	ds_write_b32 v7, v5 offset:45056
	s_and_saveexec_b64 s[14:15], s[40:41]
	v_mov_b32_e32 v5, s35
	v_mov_b32_e32 v7, s8
	v_mov_b32_e32 v8, s13
	v_add_u32_e32 v5, 0xd000, v5
	ds_write2_b32 v5, v7, v8 offset0:2 offset1:34
	s_or_b64 exec, exec, s[14:15]
	v_mul_f32_e64 v5, |v6|, s97
	v_rndne_f32_e32 v7, v5
	v_sub_f32_e32 v8, v5, v7
	v_fma_f32 v5, |v6|, s97, -v5
	s_mov_b32 s8, 0xb2a5705f
	v_fma_f32 v5, |v6|, s8, v5
	v_add_f32_e32 v5, v8, v5
	v_exp_f32_e32 v5, v5
	v_cvt_i32_f32_e32 v7, v7
	s_mov_b32 s8, 0x42ce8ed0
	v_cmp_ngt_f32_e64 vcc, |v6|, s8
	s_mov_b32 s8, 0xc2b17218
	v_ldexp_f32 v5, v5, v7
	v_cndmask_b32_e32 v5, 0, v5, vcc
	v_cmp_nlt_f32_e64 vcc, |v6|, s8
	v_max_f32_e32 v8, v6, v6
	s_mov_b32 s8, 0x3f2aaaab
	v_cndmask_b32_e32 v5, v247, v5, vcc
	v_add_f32_e32 v9, 1.0, v5
	v_add_f32_e32 v6, -1.0, v9
	v_sub_f32_e32 v7, v6, v9
	v_add_f32_e32 v7, 1.0, v7
	v_sub_f32_e32 v6, v5, v6
	v_add_f32_e32 v10, v6, v7
	v_frexp_mant_f32_e32 v11, v9
	v_cvt_f64_f32_e32 v[6:7], v9
	v_frexp_exp_i32_f64_e32 v6, v[6:7]
	v_cmp_gt_f32_e32 vcc, s8, v11
	s_mov_b32 s8, 0x3f317218
	v_min_f32_e32 v8, 0, v8
	v_subbrev_co_u32_e32 v6, vcc, 0, v6, vcc
	v_sub_u32_e32 v7, 0, v6
	v_ldexp_f32 v9, v9, v7
	v_ldexp_f32 v7, v10, v7
	v_add_f32_e32 v10, -1.0, v9
	v_add_f32_e32 v13, 1.0, v9
	v_add_f32_e32 v11, 1.0, v10
	v_add_f32_e32 v14, -1.0, v13
	v_sub_f32_e32 v11, v9, v11
	v_sub_f32_e32 v9, v9, v14
	v_add_f32_e32 v11, v7, v11
	v_add_f32_e32 v7, v7, v9
	v_add_f32_e32 v9, v13, v7
	v_rcp_f32_e32 v14, v9
	v_add_f32_e32 v12, v10, v11
	v_sub_f32_e32 v10, v10, v12
	v_add_f32_e32 v10, v11, v10
	v_sub_f32_e32 v11, v13, v9
	v_add_f32_e32 v7, v7, v11
	v_mul_f32_e32 v11, v12, v14
	v_mul_f32_e32 v13, v9, v11
	v_fma_f32 v15, v11, v9, -v13
	v_fmac_f32_e32 v15, v11, v7
	v_add_f32_e32 v16, v13, v15
	v_sub_f32_e32 v17, v12, v16
	v_sub_f32_e32 v12, v12, v17
	v_sub_f32_e32 v13, v16, v13
	v_sub_f32_e32 v12, v12, v16
	v_add_f32_e32 v10, v10, v12
	v_sub_f32_e32 v12, v13, v15
	v_add_f32_e32 v10, v12, v10
	v_add_f32_e32 v12, v17, v10
	v_mul_f32_e32 v13, v14, v12
	v_mul_f32_e32 v15, v9, v13
	v_fma_f32 v9, v13, v9, -v15
	v_fmac_f32_e32 v9, v13, v7
	v_sub_f32_e32 v7, v17, v12
	v_add_f32_e32 v7, v10, v7
	v_add_f32_e32 v10, v15, v9
	v_sub_f32_e32 v16, v12, v10
	v_sub_f32_e32 v12, v12, v16
	v_sub_f32_e32 v15, v10, v15
	v_sub_f32_e32 v10, v12, v10
	v_add_f32_e32 v7, v7, v10
	v_sub_f32_e32 v9, v15, v9
	v_cvt_f32_i32_e32 v6, v6
	v_add_f32_e32 v7, v9, v7
	v_add_f32_e32 v9, v11, v13
	v_add_f32_e32 v7, v16, v7
	v_sub_f32_e32 v10, v9, v11
	v_mul_f32_e32 v7, v14, v7
	v_sub_f32_e32 v10, v13, v10
	v_add_f32_e32 v7, v10, v7
	v_mul_f32_e32 v13, 0x3f317218, v6
	v_add_f32_e32 v10, v9, v7
	v_fma_f32 v14, v6, s8, -v13
	v_mul_f32_e32 v11, v10, v10
	v_fmac_f32_e32 v14, 0xb102e308, v6
	v_sub_f32_e32 v6, v10, v9
	v_fmamk_f32 v12, v11, 0x3e9b6dac, v227
	v_sub_f32_e32 v6, v7, v6
	v_add_f32_e32 v7, v13, v14
	v_fmaak_f32 v12, v11, v12, 0x3f2aaada
	v_sub_f32_e32 v9, v7, v13
	v_ldexp_f32 v13, v10, 1
	v_mul_f32_e32 v10, v10, v11
	v_mul_f32_e32 v10, v10, v12
	v_add_f32_e32 v11, v13, v10
	v_sub_f32_e32 v12, v11, v13
	v_ldexp_f32 v6, v6, 1
	v_sub_f32_e32 v10, v10, v12
	v_add_f32_e32 v6, v6, v10
	v_add_f32_e32 v10, v11, v6
	v_sub_f32_e32 v11, v10, v11
	v_sub_f32_e32 v6, v6, v11
	v_add_f32_e32 v11, v7, v10
	v_sub_f32_e32 v12, v11, v7
	v_sub_f32_e32 v13, v11, v12
	v_sub_f32_e32 v9, v14, v9
	v_sub_f32_e32 v7, v7, v13
	v_sub_f32_e32 v10, v10, v12
	v_add_f32_e32 v7, v10, v7
	v_add_f32_e32 v10, v9, v6
	v_sub_f32_e32 v12, v10, v9
	v_sub_f32_e32 v13, v10, v12
	v_sub_f32_e32 v9, v9, v13
	v_sub_f32_e32 v6, v6, v12
	v_add_f32_e32 v7, v10, v7
	v_add_f32_e32 v6, v6, v9
	v_add_f32_e32 v9, v11, v7
	v_sub_f32_e32 v10, v9, v11
	v_sub_f32_e32 v7, v7, v10
	v_add_f32_e32 v6, v6, v7
	s_mov_b32 s8, 0x7f800000
	v_add_f32_e32 v6, v9, v6
	v_cmp_neq_f32_e32 vcc, s8, v5
	s_mov_b32 s8, 0x33800000
	s_nop 0
	v_cndmask_b32_e32 v6, v247, v6, vcc
	v_cmp_lt_f32_e64 vcc, |v5|, s8
	s_nop 1
	v_cndmask_b32_e32 v5, v6, v5, vcc
	v_sub_f32_e32 v5, v8, v5
	ds_bpermute_b32 v6, v77, v5
	s_waitcnt lgkmcnt(0)
; __device__ __forceinline__ float rdlane(float v, int l) { return __builtin_bit_cast(float, __builtin_amdgcn_readlane(__builtin_bit_cast(int, v), l)); }
; __device__ __forceinline__ float bperm(float v, int srclane) { return __builtin_bit_cast(float, __builtin_amdgcn_ds_bpermute(srclane << 2, __builtin_bit_cast(int, v))); }
; __device__ __forceinline__ void mseq_item(Frame& F, int L, int item) {
;     ...
;         for (int o = 1; o < 64; o <<= 1) { const float t = bperm(bc, F.lane - o); if (F.lane >= o) bc += t; }
;         const float bend = rdlane(bc, 63); const float g = igv[i] + bend - bc; const float gm = wave_max(g);
;         sg[c * 64 + F.lane] = g; if (F.lane == 0) { sbend[c] = bend; sgmax[c] = gm; } } }
;     __syncthreads();
;     if (F.wave == 0) { const int c = F.lane & 31; const float bend = sbend[c], gmx = sgmax[c]; float a = bend, bq = gmx;
; #pragma unroll
;         for (int o = 1; o < 32; o <<= 1) { const float ta = bperm(a, F.lane - o), tb = bperm(bq, F.lane - o); if ((F.lane & 31) >= o) { bq = fmaxf(tb + a, bq); a = ta + a; } }
;         const float mn = fmaxf(a, bq);
;         float mp = bperm(mn, F.lane - 1); if ((F.lane & 31) == 0) mp = 0.f;
;         if (F.lane < 32) { sdec[c] = expf(bend + mp - mn); smn[c] = mn; if (vs == 0) { WSP(float, WS_MC)[bh * 32 + c] = mp; if (c == 31) F.out[O_MP + (size_t)L * 32 + bh] = mn; } } }
	v_add_f32_e32 v6, v5, v6
	v_cndmask_b32_e64 v5, v6, v5, s[42:43]
	ds_bpermute_b32 v6, v101, v5
	s_waitcnt lgkmcnt(0)
	v_add_f32_e32 v6, v5, v6
	v_cndmask_b32_e64 v5, v6, v5, s[44:45]
	ds_bpermute_b32 v6, v103, v5
	s_waitcnt lgkmcnt(0)
	v_add_f32_e32 v6, v5, v6
	v_cndmask_b32_e64 v5, v6, v5, s[46:47]
	ds_bpermute_b32 v6, v110, v5
	s_waitcnt lgkmcnt(0)
	v_add_f32_e32 v6, v5, v6
	v_cndmask_b32_e64 v5, v6, v5, s[48:49]
	ds_bpermute_b32 v6, v111, v5
	s_waitcnt lgkmcnt(0)
	v_add_f32_e32 v6, v5, v6
	v_cndmask_b32_e64 v5, v6, v5, s[50:51]
	ds_bpermute_b32 v6, v112, v5
	s_waitcnt lgkmcnt(0)
	v_add_f32_e32 v6, v5, v6
	v_cndmask_b32_e64 v5, v6, v5, s[52:53]
	s_nop 0
	v_readlane_b32 s8, v5, 63
	s_nop 1
	v_add_f32_e32 v4, s8, v4
	v_sub_f32_e32 v4, v4, v5
	v_mov_b32_e32 v5, v4
	s_nop 1
	v_mov_b32_dpp v5, v5 quad_perm:[1,0,3,2] row_mask:0xf bank_mask:0xf
	v_max_f32_e32 v5, v5, v5
	v_max_f32_e32 v5, v4, v5
	v_mov_b32_e32 v6, v5
	s_nop 1
	v_mov_b32_dpp v6, v6 quad_perm:[2,3,0,1] row_mask:0xf bank_mask:0xf
	v_max_f32_e32 v6, v6, v6
	v_max_f32_e32 v5, v5, v6
	v_mov_b32_e32 v6, v5
	s_nop 1
	v_mov_b32_dpp v6, v6 row_half_mirror row_mask:0xf bank_mask:0xf
	v_max_f32_e32 v6, v6, v6
	v_max_f32_e32 v5, v5, v6
	v_mov_b32_e32 v6, v5
	s_nop 1
	v_mov_b32_dpp v6, v6 row_mirror row_mask:0xf bank_mask:0xf
	v_max_f32_e32 v6, v6, v6
	v_max_f32_e32 v5, v5, v6
	v_mov_b32_e32 v6, v5
	s_nop 1
	v_mov_b32_dpp v6, v6 row_bcast:15 row_mask:0xa bank_mask:0xf
	v_max_f32_e32 v6, v6, v6
	v_max_f32_e32 v5, v5, v6
	v_mov_b32_e32 v6, v5
	s_nop 1
	v_mov_b32_dpp v6, v6 row_bcast:31 row_mask:0xc bank_mask:0xf
	v_max_f32_e32 v6, v6, v6
	v_max_f32_e32 v5, v5, v6
	s_nop 0
	v_readlane_b32 s13, v5, 63
	v_add_u32_e32 v5, s38, v75
	ds_write_b32 v5, v4 offset:45056
	s_and_saveexec_b64 s[14:15], s[40:41]
	v_mov_b32_e32 v4, s35
	v_mov_b32_e32 v5, s8
	v_mov_b32_e32 v6, s13
	v_add_u32_e32 v4, 0xd000, v4
	ds_write2_b32 v4, v5, v6 offset0:3 offset1:35
	s_or_b64 exec, exec, s[14:15]
	s_and_b32 s77, s75, 7
	s_andn2_b64 vcc, exec, s[0:1]
	s_waitcnt lgkmcnt(0)
	s_barrier
	s_cbranch_vccnz .LBB0_640
	v_add_u32_e32 v6, 0xd000, v114
	ds_read2_b32 v[4:5], v6 offset1:32
	s_waitcnt lgkmcnt(0)
	ds_bpermute_b32 v8, v77, v5
	ds_bpermute_b32 v7, v77, v4
	v_max_f32_e32 v9, v5, v5
	s_waitcnt lgkmcnt(1)
	v_add_f32_e32 v8, v4, v8
	v_max_f32_e32 v8, v8, v9
	v_cndmask_b32_e64 v5, v8, v5, s[54:55]
	ds_bpermute_b32 v9, v101, v5
	s_waitcnt lgkmcnt(1)
	v_add_f32_e32 v7, v4, v7
	v_cndmask_b32_e64 v7, v7, v4, s[54:55]
	ds_bpermute_b32 v8, v101, v7
	v_max_f32_e32 v10, v5, v5
	s_waitcnt lgkmcnt(1)
	v_add_f32_e32 v9, v7, v9
	v_max_f32_e32 v9, v9, v10
	v_cndmask_b32_e64 v5, v9, v5, s[56:57]
	ds_bpermute_b32 v9, v103, v5
	s_waitcnt lgkmcnt(1)
	v_add_f32_e32 v8, v7, v8
	v_cndmask_b32_e64 v7, v8, v7, s[56:57]
	ds_bpermute_b32 v8, v103, v7
	v_max_f32_e32 v10, v5, v5
	s_waitcnt lgkmcnt(1)
	v_add_f32_e32 v9, v7, v9
	v_max_f32_e32 v9, v9, v10
	v_cndmask_b32_e64 v5, v9, v5, s[58:59]
	s_waitcnt lgkmcnt(0)
	v_add_f32_e32 v8, v7, v8
	ds_bpermute_b32 v9, v110, v5
	v_cndmask_b32_e64 v7, v8, v7, s[58:59]
	ds_bpermute_b32 v8, v110, v7
	v_max_f32_e32 v10, v5, v5
	s_waitcnt lgkmcnt(1)
	v_add_f32_e32 v9, v7, v9
	v_max_f32_e32 v9, v9, v10
	s_waitcnt lgkmcnt(0)
	v_add_f32_e32 v8, v7, v8
	v_cndmask_b32_e64 v5, v9, v5, s[60:61]
	v_cndmask_b32_e64 v7, v8, v7, s[60:61]
	ds_bpermute_b32 v9, v111, v5
	ds_bpermute_b32 v8, v111, v7
	v_max_f32_e32 v10, v5, v5
	s_waitcnt lgkmcnt(1)
	v_add_f32_e32 v9, v7, v9
	v_max_f32_e32 v9, v9, v10
	s_waitcnt lgkmcnt(0)
	v_add_f32_e32 v8, v7, v8
	v_cndmask_b32_e64 v5, v9, v5, s[26:27]
	v_cndmask_b32_e64 v7, v8, v7, s[26:27]
	v_max_f32_e32 v7, v7, v7
	v_max_f32_e32 v5, v5, v5
	v_max_f32_e32 v5, v7, v5
	ds_bpermute_b32 v7, v77, v5
	s_and_saveexec_b64 s[14:15], s[52:53]
	s_cbranch_execz .LBB0_639
	s_waitcnt lgkmcnt(0)
	v_cndmask_b32_e64 v7, v7, 0, s[54:55]
	v_add_f32_e32 v4, v4, v7
	v_sub_f32_e32 v4, v4, v5
	v_mul_f32_e32 v8, 0x3fb8aa3b, v4
	v_fma_f32 v9, v4, s93, -v8
	v_rndne_f32_e32 v10, v8
	v_fmac_f32_e32 v9, 0x32a5705f, v4
	v_sub_f32_e32 v8, v8, v10
	v_add_f32_e32 v8, v8, v9
	v_cvt_i32_f32_e32 v9, v10
	v_exp_f32_e32 v8, v8
	s_mov_b32 s8, 0xc2ce8ed0
	v_cmp_ngt_f32_e32 vcc, s8, v4
	s_mov_b32 s8, 0x42b17218
	v_ldexp_f32 v8, v8, v9
	v_cndmask_b32_e32 v8, 0, v8, vcc
	v_cmp_nlt_f32_e32 vcc, s8, v4
	s_cmp_lg_u32 s77, 0
	s_nop 0
	v_cndmask_b32_e32 v4, v247, v8, vcc
	ds_write2_b32 v6, v4, v5 offset0:64 offset1:96
	s_cbranch_scc1 .LBB0_639
	v_lshl_or_b32 v8, s12, 5, v113
	v_ashrrev_i32_e32 v9, 31, v8
	v_lshl_add_u64 v[8:9], v[8:9], 2, s[2:3]
	global_store_dword v[8:9], v7, off
	s_and_b64 exec, exec, s[64:65]
	s_cbranch_execz .LBB0_639
	s_ashr_i32 s13, s12, 31
	s_lshl_b64 s[16:17], s[12:13], 2
	s_add_u32 s16, s39, s16
	s_addc_u32 s17, s72, s17
	global_store_dword v2, v5, s[16:17]

; #define LAS __attribute__((address_space(3)))
; __device__ __forceinline__ void stage_wig(CArgs& A, Frame& F, int L) {
;     const float* w_in = A.in[9] + (size_t)L * D * DIN; LAS float* wig = (LAS float*)(F.lds + WIG_OFF);
;     float t[16];
; #pragma unroll
;     for (int q = 0; q < 16; ++q) { const int i = F.tid + NT * q; t[q] = w_in[(size_t)(i >> 3) * DIN + 3072 + (i & 7)]; }
; #pragma unroll
;     for (int q = 0; q < 16; ++q) { const int i = F.tid + NT * q; wig[(i & 7) * 1024 + (i >> 3)] = t[q]; }
; }
; __global__ void __launch_bounds__(NT, 2) fwd(const Args args) {
;     ...
;         if (IN(pb + 10)) { PHASE_BEGIN
;             const float* g = A.in[17] + ((size_t)L * 3 + 2) * D; const float* bb = A.in[18] + ((size_t)L * 3 + 2) * D; const bf16* X = WSP(bf16, WS_XB);
;             if (L + 1 < DEPTH) { stage_wig(A, F, L + 1); __syncthreads(); }
.LBB0_1690:
	v_readlane_b32 s0, v253, 1
	v_readlane_b32 s2, v253, 3
	v_readlane_b32 s1, v253, 2
	v_readlane_b32 s3, v253, 4
	s_cmp_le_i32 s2, s8
	s_cselect_b64 s[0:1], -1, 0
	s_cmp_lt_i32 s8, s3
	s_cselect_b64 s[2:3], -1, 0
	s_and_b64 s[0:1], s[0:1], s[2:3]
	s_andn2_b64 vcc, exec, s[0:1]
	s_cbranch_vccnz .LBB0_1723
	v_readlane_b32 s2, v253, 5
	v_readlane_b32 s10, v254, 41
	v_readlane_b32 s3, v253, 6
	s_mov_b32 s4, s9
	s_load_dwordx4 s[56:59], s[2:3], 0xe0
	v_readlane_b32 s6, v253, 11
	v_mbcnt_lo_u32_b32 v0, -1, s4
	v_mbcnt_hi_u32_b32 v0, -1, v0
	v_readlane_b32 s8, v253, 0
	s_load_dwordx4 s[40:43], s[2:3], 0x88
	s_add_i32 s7, s10, 1
	s_cmp_gt_i32 s10, 2
	s_cselect_b64 s[4:5], -1, 0
	s_and_b64 vcc, exec, s[4:5]
	s_cbranch_vccnz .LBB0_1693
	s_load_dwordx2 s[12:13], s[2:3], 0x48
	s_mul_i32 s14, s7, 0x1a08000
	s_mul_hi_i32 s11, s7, 0x1a08000
	v_lshl_add_u32 v1, s6, 6, v0
	v_and_b32_e32 v3, 7, v0
	s_waitcnt lgkmcnt(0)
	s_add_u32 s12, s12, s14
	s_addc_u32 s13, s13, s11
	v_ashrrev_i32_e32 v10, 3, v1
	v_mov_b64_e32 v[4:5], s[12:13]
	s_movk_i32 s11, 0x6820
	v_mad_i64_i32 v[6:7], s[12:13], v10, s11, v[4:5]
	v_lshlrev_b32_e32 v8, 2, v3
	v_mov_b32_e32 v9, v2
	v_lshl_add_u64 v[6:7], v[6:7], 0, v[8:9]
	s_movk_i32 s14, 0x3000
	v_add_co_u32_e32 v6, vcc, s14, v6
	s_nop 1
	v_addc_co_u32_e32 v7, vcc, 0, v7, vcc
	global_load_dword v3, v[6:7], off
	v_add_u32_e32 v6, 0x200, v1
	v_ashrrev_i32_e32 v11, 3, v6
	v_mad_i64_i32 v[6:7], s[12:13], v11, s11, v[4:5]
	v_lshl_add_u64 v[6:7], v[6:7], 0, v[8:9]
	v_add_co_u32_e32 v6, vcc, s14, v6
	s_nop 1
	v_addc_co_u32_e32 v7, vcc, 0, v7, vcc
	global_load_dword v12, v[6:7], off
	v_add_u32_e32 v6, 0x400, v1
	s_waitcnt vmcnt(2)
	v_ashrrev_i32_e32 v13, 3, v6
	v_mad_i64_i32 v[6:7], s[12:13], v13, s11, v[4:5]
	v_lshl_add_u64 v[6:7], v[6:7], 0, v[8:9]
	v_add_co_u32_e32 v6, vcc, s14, v6
	s_nop 1
	v_addc_co_u32_e32 v7, vcc, 0, v7, vcc
	global_load_dword v14, v[6:7], off
	v_add_u32_e32 v6, 0x600, v1
	v_ashrrev_i32_e32 v15, 3, v6
	v_mad_i64_i32 v[6:7], s[12:13], v15, s11, v[4:5]
	v_lshl_add_u64 v[6:7], v[6:7], 0, v[8:9]
	v_add_co_u32_e32 v6, vcc, s14, v6
	s_nop 1
	v_addc_co_u32_e32 v7, vcc, 0, v7, vcc
	global_load_dword v16, v[6:7], off
	v_add_u32_e32 v6, 0x800, v1
	v_ashrrev_i32_e32 v17, 3, v6
	v_mad_i64_i32 v[6:7], s[12:13], v17, s11, v[4:5]
	v_lshl_add_u64 v[6:7], v[6:7], 0, v[8:9]
	v_add_co_u32_e32 v6, vcc, s14, v6
	s_nop 1
	v_addc_co_u32_e32 v7, vcc, 0, v7, vcc
	global_load_dword v18, v[6:7], off
	v_add_u32_e32 v6, 0xa00, v1
	v_ashrrev_i32_e32 v19, 3, v6
	v_mad_i64_i32 v[6:7], s[12:13], v19, s11, v[4:5]
	v_lshl_add_u64 v[6:7], v[6:7], 0, v[8:9]
	v_add_co_u32_e32 v6, vcc, s14, v6
	s_nop 1
	v_addc_co_u32_e32 v7, vcc, 0, v7, vcc
	global_load_dword v20, v[6:7], off
	v_add_u32_e32 v6, 0xc00, v1
	v_ashrrev_i32_e32 v21, 3, v6
	v_mad_i64_i32 v[6:7], s[12:13], v21, s11, v[4:5]
	v_lshl_add_u64 v[6:7], v[6:7], 0, v[8:9]
	v_add_co_u32_e32 v6, vcc, s14, v6
	s_nop 1
	v_addc_co_u32_e32 v7, vcc, 0, v7, vcc
	global_load_dword v22, v[6:7], off
	v_add_u32_e32 v6, 0xe00, v1
	v_ashrrev_i32_e32 v23, 3, v6
	v_mad_i64_i32 v[6:7], s[12:13], v23, s11, v[4:5]
	v_lshl_add_u64 v[6:7], v[6:7], 0, v[8:9]
	v_add_co_u32_e32 v6, vcc, s14, v6
	s_nop 1
	v_addc_co_u32_e32 v7, vcc, 0, v7, vcc
	global_load_dword v24, v[6:7], off
	v_add_u32_e32 v6, 0x1000, v1
	v_ashrrev_i32_e32 v25, 3, v6
	v_mad_i64_i32 v[6:7], s[12:13], v25, s11, v[4:5]
	v_lshl_add_u64 v[6:7], v[6:7], 0, v[8:9]
	v_add_co_u32_e32 v6, vcc, s14, v6
	s_nop 1
	v_addc_co_u32_e32 v7, vcc, 0, v7, vcc
	global_load_dword v26, v[6:7], off
	v_add_u32_e32 v6, 0x1200, v1
	v_ashrrev_i32_e32 v27, 3, v6
	v_mad_i64_i32 v[6:7], s[12:13], v27, s11, v[4:5]
	v_lshl_add_u64 v[6:7], v[6:7], 0, v[8:9]
	v_add_co_u32_e32 v6, vcc, s14, v6
	s_nop 1
	v_addc_co_u32_e32 v7, vcc, 0, v7, vcc
	global_load_dword v28, v[6:7], off
	v_add_u32_e32 v6, 0x1400, v1
	v_ashrrev_i32_e32 v29, 3, v6
	v_mad_i64_i32 v[6:7], s[12:13], v29, s11, v[4:5]
	v_lshl_add_u64 v[6:7], v[6:7], 0, v[8:9]
	v_add_co_u32_e32 v6, vcc, s14, v6
	s_nop 1
	v_addc_co_u32_e32 v7, vcc, 0, v7, vcc
	global_load_dword v30, v[6:7], off
	v_add_u32_e32 v6, 0x1600, v1
	v_ashrrev_i32_e32 v31, 3, v6
	v_mad_i64_i32 v[6:7], s[12:13], v31, s11, v[4:5]
	v_lshl_add_u64 v[6:7], v[6:7], 0, v[8:9]
	v_add_co_u32_e32 v6, vcc, s14, v6
	s_nop 1
	v_addc_co_u32_e32 v7, vcc, 0, v7, vcc
	global_load_dword v32, v[6:7], off
	v_add_u32_e32 v6, 0x1800, v1
	v_ashrrev_i32_e32 v33, 3, v6
	v_mad_i64_i32 v[6:7], s[12:13], v33, s11, v[4:5]
	v_lshl_add_u64 v[6:7], v[6:7], 0, v[8:9]
	v_add_co_u32_e32 v6, vcc, s14, v6
	s_nop 1
	v_addc_co_u32_e32 v7, vcc, 0, v7, vcc
	global_load_dword v34, v[6:7], off
	v_add_u32_e32 v6, 0x1a00, v1
	v_ashrrev_i32_e32 v35, 3, v6
	v_mad_i64_i32 v[6:7], s[12:13], v35, s11, v[4:5]
	v_lshl_add_u64 v[6:7], v[6:7], 0, v[8:9]
	v_add_co_u32_e32 v6, vcc, s14, v6
	s_nop 1
	v_addc_co_u32_e32 v7, vcc, 0, v7, vcc
	global_load_dword v36, v[6:7], off
	v_add_u32_e32 v6, 0x1c00, v1
	v_ashrrev_i32_e32 v37, 3, v6
	v_mad_i64_i32 v[6:7], s[12:13], v37, s11, v[4:5]
	v_add_u32_e32 v1, 0x1e00, v1
	v_lshl_add_u64 v[6:7], v[6:7], 0, v[8:9]
	v_ashrrev_i32_e32 v1, 3, v1
	v_add_co_u32_e32 v6, vcc, s14, v6
	v_mad_i64_i32 v[4:5], s[12:13], v1, s11, v[4:5]
	s_nop 0
	v_addc_co_u32_e32 v7, vcc, 0, v7, vcc
	v_lshl_add_u64 v[4:5], v[4:5], 0, v[8:9]
	v_add_co_u32_e32 v4, vcc, s14, v4
	global_load_dword v6, v[6:7], off
	s_nop 0
	v_addc_co_u32_e32 v5, vcc, 0, v5, vcc
	global_load_dword v4, v[4:5], off
	v_lshlrev_b32_e32 v5, 12, v0
	s_add_i32 s11, 0, 0x12000
	v_and_b32_e32 v5, 0x7000, v5
	v_add_u32_e32 v5, s11, v5
	v_lshl_add_u32 v7, v10, 2, v5
	s_waitcnt vmcnt(15)
	ds_write_b32 v7, v3
	v_lshl_add_u32 v3, v11, 2, v5
	s_waitcnt vmcnt(14)
	ds_write_b32 v3, v12
	v_lshl_add_u32 v3, v13, 2, v5
	s_waitcnt vmcnt(13)
	ds_write_b32 v3, v14
	v_lshl_add_u32 v3, v15, 2, v5
	s_waitcnt vmcnt(12)
	ds_write_b32 v3, v16
	v_lshl_add_u32 v3, v17, 2, v5
	s_waitcnt vmcnt(11)
	ds_write_b32 v3, v18
	v_lshl_add_u32 v3, v19, 2, v5
	s_waitcnt vmcnt(10)
	ds_write_b32 v3, v20
	v_lshl_add_u32 v3, v21, 2, v5
	s_waitcnt vmcnt(9)
	ds_write_b32 v3, v22
	v_lshl_add_u32 v3, v23, 2, v5
	s_waitcnt vmcnt(8)
	ds_write_b32 v3, v24
	v_lshl_add_u32 v3, v25, 2, v5
	s_waitcnt vmcnt(7)
	ds_write_b32 v3, v26
	v_lshl_add_u32 v3, v27, 2, v5
	s_waitcnt vmcnt(6)
	ds_write_b32 v3, v28
	v_lshl_add_u32 v3, v29, 2, v5
	v_lshl_add_u32 v1, v1, 2, v5
	s_waitcnt vmcnt(5)
	ds_write_b32 v3, v30
	v_lshl_add_u32 v3, v31, 2, v5
	s_waitcnt vmcnt(4)
	ds_write_b32 v3, v32
	v_lshl_add_u32 v3, v33, 2, v5
	s_waitcnt vmcnt(3)
	ds_write_b32 v3, v34
	v_lshl_add_u32 v3, v35, 2, v5
	s_waitcnt vmcnt(2)
	ds_write_b32 v3, v36
	v_lshl_add_u32 v3, v37, 2, v5
	s_waitcnt vmcnt(1)
	ds_write_b32 v3, v6
	s_waitcnt vmcnt(0)
	ds_write_b32 v1, v4
	s_waitcnt lgkmcnt(0)
	s_barrier
